# Merged-V attention: second-half P.V MFMAs moved into the DMA-issue / row-max window of the steady-state steps (reads issued during the QK phase)
# speedup vs baseline: 1.0530x; 1.0025x over previous
.LBB0_237:
	v_add_u32_e32 v0, s2, v220
	s_mov_b32 s98, s2
	ds_read_b64_tr_b16 v[192:193], v0 offset:24576
	ds_read_b64_tr_b16 v[194:195], v0 offset:25088
	s_waitcnt lgkmcnt(9)
	v_mfma_f32_32x32x16_bf16 v[112:127], v[188:191], v[144:147], v[48:63]
	v_add_f32_e32 v2, v80, v81
	v_add_f32_e32 v2, v82, v2
	v_add_f32_e32 v2, v83, v2
	v_add_f32_e32 v2, v84, v2
	v_add_f32_e32 v2, v85, v2
	v_cvt_pk_bf16_f32 v156, v80, v81
	v_cvt_pk_bf16_f32 v157, v82, v83
	ds_read_b64_tr_b16 v[188:189], v0 offset:28672
	ds_read_b64_tr_b16 v[190:191], v0 offset:29184
	s_waitcnt lgkmcnt(10)
	v_mfma_f32_32x32x16_bf16 v[96:111], v[184:187], v[144:147], v[48:63]
	v_add_f32_e32 v2, v86, v2
	v_add_f32_e32 v2, v87, v2
	v_add_f32_e32 v2, v88, v2
	v_add_f32_e32 v2, v89, v2
	v_cvt_pk_bf16_f32 v158, v84, v85
	v_cvt_pk_bf16_f32 v159, v86, v87
	ds_read_b64_tr_b16 v[184:185], v0 offset:25600
	ds_read_b64_tr_b16 v[186:187], v0 offset:26112
	s_waitcnt lgkmcnt(11)
	v_mfma_f32_32x32x16_bf16 v[112:127], v[180:183], v[136:139], v[112:127]
	v_add_u32_e32 v3, s98, v220
	v_add_u32_e32 v3, 0xf000, v3
	ds_read_b64_tr_b16 v[180:181], v3 offset:24576
	ds_read_b64_tr_b16 v[182:183], v3 offset:25088
	v_add_f32_e32 v2, v90, v2
	v_add_f32_e32 v2, v91, v2
	v_add_f32_e32 v2, v92, v2
	v_add_f32_e32 v2, v93, v2
	v_cvt_pk_bf16_f32 v152, v88, v89
	v_cvt_pk_bf16_f32 v153, v90, v91
	ds_read_b64_tr_b16 v[84:85], v0 offset:29696
	ds_read_b64_tr_b16 v[86:87], v0 offset:30208
	s_waitcnt lgkmcnt(12)
	v_mfma_f32_32x32x16_bf16 v[96:111], v[176:179], v[136:139], v[96:111]
	ds_read_b64_tr_b16 v[88:89], v3 offset:28672
	ds_read_b64_tr_b16 v[90:91], v3 offset:29184
	ds_read_b64_tr_b16 v[176:177], v3 offset:25600
	ds_read_b64_tr_b16 v[178:179], v3 offset:26112
	v_add_f32_e32 v2, v94, v2
	v_add_f32_e32 v2, v95, v2
	v_add_f32_e32 v2, v64, v2
	v_add_f32_e32 v2, v65, v2
	v_cvt_pk_bf16_f32 v154, v92, v93
	v_cvt_pk_bf16_f32 v155, v94, v95
	ds_read_b64_tr_b16 v[80:81], v0 offset:26624
	ds_read_b64_tr_b16 v[82:83], v0 offset:27136
	s_waitcnt lgkmcnt(13)
	v_mfma_f32_32x32x16_bf16 v[112:127], v[172:175], v[132:135], v[112:127]
	ds_read_b64_tr_b16 v[92:93], v3 offset:29696
	ds_read_b64_tr_b16 v[94:95], v3 offset:30208
	ds_read_b64_tr_b16 v[172:173], v3 offset:26624
	ds_read_b64_tr_b16 v[174:175], v3 offset:27136
	v_add_f32_e32 v2, v66, v2
	v_add_f32_e32 v2, v67, v2
	v_add_f32_e32 v2, v68, v2
	v_add_f32_e32 v2, v69, v2
	v_cvt_pk_bf16_f32 v148, v64, v65
	v_cvt_pk_bf16_f32 v149, v66, v67
	ds_read_b64_tr_b16 v[10:11], v0 offset:30720
	ds_read_b64_tr_b16 v[12:13], v0 offset:31232
	s_waitcnt lgkmcnt(14)
	v_mfma_f32_32x32x16_bf16 v[96:111], v[168:171], v[132:135], v[96:111]
	ds_read_b64_tr_b16 v[168:169], v3 offset:30720
	ds_read_b64_tr_b16 v[170:171], v3 offset:31232
	v_add_f32_e32 v2, v70, v2
	v_add_f32_e32 v2, v71, v2
	v_add_f32_e32 v2, v72, v2
	v_add_f32_e32 v2, v73, v2
	v_cvt_pk_bf16_f32 v150, v68, v69
	v_cvt_pk_bf16_f32 v151, v70, v71
	ds_read_b64_tr_b16 v[6:7], v0 offset:27648
	ds_read_b64_tr_b16 v[8:9], v0 offset:28160
	s_waitcnt lgkmcnt(14)
	v_mfma_f32_32x32x16_bf16 v[112:127], v[164:167], v[128:131], v[112:127]
	ds_read_b64_tr_b16 v[66:67], v3 offset:27648
	ds_read_b64_tr_b16 v[68:69], v3 offset:28160
	ds_read_b64_tr_b16 v[164:165], v3 offset:31744
	ds_read_b64_tr_b16 v[166:167], v3 offset:32256
	v_add_f32_e32 v2, v74, v2
	v_add_f32_e32 v2, v75, v2
	v_add_f32_e32 v2, v76, v2
	v_add_f32_e32 v14, v77, v2
	v_cvt_pk_bf16_f32 v140, v72, v73
	v_cvt_pk_bf16_f32 v141, v74, v75
	ds_read_b64_tr_b16 v[2:3], v0 offset:31744
	ds_read_b64_tr_b16 v[4:5], v0 offset:32256
	v_mfma_f32_32x32x16_bf16 v[96:111], v[160:163], v[128:131], v[96:111]
	v_add_f32_e32 v0, v78, v14
	v_add_f32_e32 v0, v79, v0
	v_add_f32_e32 v0, 0, v0
	v_cvt_pk_bf16_f32 v142, v76, v77
	v_cvt_pk_bf16_f32 v143, v78, v79
	v_lshl_add_u64 v[14:15], v[202:203], 0, s[26:27]
	s_add_i32 s2, s47, s61
	s_waitcnt lgkmcnt(14)
	v_mfma_f32_32x32x16_bf16 v[224:239], v[156:159], v[180:183], v[224:239]
	s_mov_b32 s3, m0
	s_mov_b32 m0, s2
	s_nop 0
	global_load_lds_dwordx4 v[14:15], off
	s_mov_b32 m0, s3
	v_lshl_add_u64 v[14:15], v[200:201], 0, s[26:27]
	s_add_i32 s2, s45, s62
	s_add_i32 s100, s45, s99
	s_waitcnt lgkmcnt(14)
	v_mfma_f32_32x32x16_bf16 v[240:255], v[156:159], v[88:91], v[240:255]
	s_mov_b32 s3, m0
	s_mov_b32 m0, s2
	s_nop 0
	global_load_lds_dwordx4 v[14:15], off
	s_waitcnt lgkmcnt(14)
	v_mfma_f32_32x32x16_bf16 v[224:239], v[152:155], v[176:179], v[224:239]
	s_mov_b32 m0, s100
	v_lshl_add_u64 v[64:65], v[14:15], 0, 64
	v_lshl_add_u64 v[64:65], v[64:65], 0, 64
	global_load_lds_dwordx4 v[64:65], off
	s_mov_b32 m0, s3
	v_max_f32_e32 v14, v113, v113
	v_max_f32_e32 v15, v112, v112
	s_waitcnt lgkmcnt(14)
	v_mfma_f32_32x32x16_bf16 v[240:255], v[152:155], v[92:95], v[240:255]
	v_max_f32_e32 v14, v15, v14
	v_max3_f32 v15, v114, v115, v97
	v_max3_f32 v14, v14, v96, v98
	v_max3_f32 v14, v14, v99, v116
	s_waitcnt lgkmcnt(12)
	v_mfma_f32_32x32x16_bf16 v[224:239], v[148:151], v[172:175], v[224:239]
	v_max3_f32 v15, v15, v118, v119
	v_max3_f32 v14, v14, v117, v100
	v_max3_f32 v15, v15, v102, v103
	v_max3_f32 v14, v14, v101, v120
	s_waitcnt lgkmcnt(8)
	v_mfma_f32_32x32x16_bf16 v[240:255], v[148:151], v[168:171], v[240:255]
	v_max3_f32 v15, v15, v122, v123
	v_max3_f32 v14, v14, v121, v104
	v_max3_f32 v15, v15, v106, v107
	v_max3_f32 v14, v14, v105, v124
	v_max3_f32 v15, v15, v126, v127
	s_waitcnt lgkmcnt(4)
	v_mfma_f32_32x32x16_bf16 v[224:239], v[140:143], v[66:69], v[224:239]
	v_max3_f32 v64, v14, v125, v108
	v_max3_f32 v15, v15, v110, v111
	v_add_f32_e32 v14, v222, v0
	v_max3_f32 v0, v64, v109, v15
	v_mov_b32_e32 v15, v0
	s_nop 1
	v_permlane32_swap_b32_e32 v0, v15
	s_waitcnt lgkmcnt(2)
	v_mfma_f32_32x32x16_bf16 v[240:255], v[140:143], v[164:167], v[240:255]
	v_max_f32_e32 v15, v15, v15
	v_max_f32_e32 v0, v0, v0
	v_max_f32_e32 v0, v0, v15
	v_cmp_lt_f32_e32 vcc, s52, v0
	s_cmp_lg_u64 vcc, 0
	s_cselect_b64 s[2:3], -1, 0
	s_cbranch_vccnz .LBB0_245
.LBB0_238:
	s_waitcnt lgkmcnt(14)
	v_mfma_f32_32x32x16_bf16 v[32:47], v[156:159], v[192:195], v[32:47]
	v_exp_f32_e32 v112, v112
	v_exp_f32_e32 v113, v113
	v_exp_f32_e32 v114, v114
	v_exp_f32_e32 v115, v115
	s_waitcnt lgkmcnt(12)
	v_mfma_f32_32x32x16_bf16 v[16:31], v[156:159], v[188:191], v[16:31]
	v_exp_f32_e32 v116, v116
	v_exp_f32_e32 v117, v117
	v_exp_f32_e32 v118, v118
	v_exp_f32_e32 v119, v119
	v_add_u32_e32 v0, s45, v219
	ds_read_b128 v[64:67], v0
	ds_read_b128 v[160:163], v0 offset:512
	s_waitcnt lgkmcnt(12)
	v_mfma_f32_32x32x16_bf16 v[32:47], v[152:155], v[184:187], v[32:47]
	v_exp_f32_e32 v120, v120
	v_exp_f32_e32 v121, v121
	v_exp_f32_e32 v122, v122
	v_exp_f32_e32 v123, v123
	ds_read_b128 v[192:195], v0 offset:2048
	ds_read_b128 v[184:187], v0 offset:2560
	s_waitcnt lgkmcnt(12)
	v_mfma_f32_32x32x16_bf16 v[16:31], v[152:155], v[84:87], v[16:31]
	v_exp_f32_e32 v124, v124
	v_exp_f32_e32 v125, v125
	v_exp_f32_e32 v126, v126
	v_exp_f32_e32 v127, v127
	ds_read_b128 v[188:191], v0 offset:4096
	ds_read_b128 v[176:179], v0 offset:4608
	s_waitcnt lgkmcnt(12)
	v_mfma_f32_32x32x16_bf16 v[32:47], v[148:151], v[80:83], v[32:47]
	v_exp_f32_e32 v96, v96
	v_exp_f32_e32 v97, v97
	v_exp_f32_e32 v98, v98
	v_exp_f32_e32 v99, v99
	ds_read_b128 v[180:183], v0 offset:6144
	ds_read_b128 v[172:175], v0 offset:6656
	s_waitcnt lgkmcnt(12)
	v_mfma_f32_32x32x16_bf16 v[16:31], v[148:151], v[10:13], v[16:31]
	v_exp_f32_e32 v100, v100
	v_exp_f32_e32 v101, v101
	v_exp_f32_e32 v102, v102
	v_exp_f32_e32 v103, v103
	s_waitcnt lgkmcnt(10)
	v_mfma_f32_32x32x16_bf16 v[32:47], v[140:143], v[6:9], v[32:47]
	v_exp_f32_e32 v104, v104
	v_exp_f32_e32 v105, v105
	v_exp_f32_e32 v106, v106
	v_exp_f32_e32 v107, v107
	s_waitcnt lgkmcnt(8)
	v_mfma_f32_32x32x16_bf16 v[16:31], v[140:143], v[2:5], v[16:31]
	v_exp_f32_e32 v108, v108
	v_exp_f32_e32 v109, v109
	v_exp_f32_e32 v110, v110
	v_exp_f32_e32 v111, v111
	s_waitcnt vmcnt(3) lgkmcnt(0)
	s_barrier
	s_andn2_b64 vcc, exec, s[2:3]
	v_add_u32_e32 v0, s60, v221
	s_cbranch_vccnz .LBB0_240
	s_waitcnt lgkmcnt(0)
	ds_read_b128 v[2:5], v0 offset:49248
	ds_read_b128 v[6:9], v0 offset:49216
	ds_read_b128 v[10:13], v0 offset:49184
	ds_read_b128 v[68:71], v0 offset:49152
	s_waitcnt lgkmcnt(3)
	v_pk_mul_f32 v[44:45], v[44:45], v[2:3]
	v_pk_mul_f32 v[236:237], v[236:237], v[2:3]
	s_waitcnt lgkmcnt(2)
	v_pk_mul_f32 v[40:41], v[40:41], v[6:7]
	v_pk_mul_f32 v[232:233], v[232:233], v[6:7]
	s_waitcnt lgkmcnt(1)
	v_pk_mul_f32 v[36:37], v[36:37], v[10:11]
	v_pk_mul_f32 v[228:229], v[228:229], v[10:11]
	v_pk_mul_f32 v[46:47], v[46:47], v[4:5]
	v_pk_mul_f32 v[238:239], v[238:239], v[4:5]
	v_pk_mul_f32 v[42:43], v[42:43], v[8:9]
	v_pk_mul_f32 v[234:235], v[234:235], v[8:9]
	v_pk_mul_f32 v[38:39], v[38:39], v[12:13]
	v_pk_mul_f32 v[230:231], v[230:231], v[12:13]
	s_waitcnt lgkmcnt(0)
	v_pk_mul_f32 v[34:35], v[34:35], v[70:71]
	v_pk_mul_f32 v[226:227], v[226:227], v[70:71]
	v_pk_mul_f32 v[32:33], v[32:33], v[68:69]
	v_pk_mul_f32 v[224:225], v[224:225], v[68:69]
	v_pk_mul_f32 v[28:29], v[28:29], v[2:3]
	v_pk_mul_f32 v[252:253], v[252:253], v[2:3]
	v_pk_mul_f32 v[24:25], v[24:25], v[6:7]
	v_pk_mul_f32 v[248:249], v[248:249], v[6:7]
	v_pk_mul_f32 v[20:21], v[20:21], v[10:11]
	v_pk_mul_f32 v[244:245], v[244:245], v[10:11]
	v_pk_mul_f32 v[30:31], v[30:31], v[4:5]
	v_pk_mul_f32 v[254:255], v[254:255], v[4:5]
	v_pk_mul_f32 v[26:27], v[26:27], v[8:9]
	v_pk_mul_f32 v[250:251], v[250:251], v[8:9]
	v_pk_mul_f32 v[22:23], v[22:23], v[12:13]
	v_pk_mul_f32 v[246:247], v[246:247], v[12:13]
	v_pk_mul_f32 v[18:19], v[18:19], v[70:71]
	v_pk_mul_f32 v[242:243], v[242:243], v[70:71]
	v_pk_mul_f32 v[16:17], v[16:17], v[68:69]
	v_pk_mul_f32 v[240:241], v[240:241], v[68:69]
.LBB0_240:
	s_add_i32 s2, s45, 0x2000
	s_cmpk_lg_i32 s45, 0x4000
	s_cselect_b32 s64, s2, 0
	v_add_u32_e32 v4, s47, v220
	s_mov_b32 s98, s47
	ds_read_b64_tr_b16 v[168:169], v4 offset:24576
	ds_read_b64_tr_b16 v[170:171], v4 offset:25088
	s_waitcnt lgkmcnt(9)
	v_mfma_f32_32x32x16_bf16 v[80:95], v[64:67], v[144:147], v[48:63]
	v_add_f32_e32 v2, v112, v113
	v_add_f32_e32 v2, v114, v2
	v_add_f32_e32 v2, v115, v2
	v_add_f32_e32 v2, v116, v2
	v_add_f32_e32 v2, v117, v2
	v_cvt_pk_bf16_f32 v156, v112, v113
	v_cvt_pk_bf16_f32 v157, v114, v115
	ds_read_b64_tr_b16 v[164:165], v4 offset:28672
	ds_read_b64_tr_b16 v[166:167], v4 offset:29184
	s_waitcnt lgkmcnt(10)
	v_mfma_f32_32x32x16_bf16 v[64:79], v[160:163], v[144:147], v[48:63]
	v_add_f32_e32 v2, v118, v2
	v_add_f32_e32 v2, v119, v2
	v_add_f32_e32 v2, v120, v2
	v_add_f32_e32 v2, v121, v2
	v_cvt_pk_bf16_f32 v158, v116, v117
	v_cvt_pk_bf16_f32 v159, v118, v119
	ds_read_b64_tr_b16 v[160:161], v4 offset:25600
	ds_read_b64_tr_b16 v[162:163], v4 offset:26112
	s_waitcnt lgkmcnt(11)
	v_mfma_f32_32x32x16_bf16 v[80:95], v[192:195], v[136:139], v[80:95]
	v_add_u32_e32 v3, s98, v220
	v_add_u32_e32 v3, 0xf000, v3
	ds_read_b64_tr_b16 v[192:193], v3 offset:24576
	ds_read_b64_tr_b16 v[194:195], v3 offset:25088
	v_add_f32_e32 v2, v122, v2
	v_add_f32_e32 v2, v123, v2
	v_add_f32_e32 v2, v124, v2
	v_add_f32_e32 v2, v125, v2
	v_cvt_pk_bf16_f32 v152, v120, v121
	v_cvt_pk_bf16_f32 v153, v122, v123
	ds_read_b64_tr_b16 v[116:117], v4 offset:29696
	ds_read_b64_tr_b16 v[118:119], v4 offset:30208
	s_waitcnt lgkmcnt(12)
	v_mfma_f32_32x32x16_bf16 v[64:79], v[184:187], v[136:139], v[64:79]
	ds_read_b64_tr_b16 v[120:121], v3 offset:28672
	ds_read_b64_tr_b16 v[122:123], v3 offset:29184
	ds_read_b64_tr_b16 v[184:185], v3 offset:25600
	ds_read_b64_tr_b16 v[186:187], v3 offset:26112
	v_add_f32_e32 v2, v126, v2
	v_add_f32_e32 v2, v127, v2
	v_add_f32_e32 v2, v96, v2
	v_add_f32_e32 v2, v97, v2
	v_cvt_pk_bf16_f32 v154, v124, v125
	v_cvt_pk_bf16_f32 v155, v126, v127
	ds_read_b64_tr_b16 v[112:113], v4 offset:26624
	ds_read_b64_tr_b16 v[114:115], v4 offset:27136
	s_waitcnt lgkmcnt(13)
	v_mfma_f32_32x32x16_bf16 v[80:95], v[188:191], v[132:135], v[80:95]
	ds_read_b64_tr_b16 v[124:125], v3 offset:29696
	ds_read_b64_tr_b16 v[126:127], v3 offset:30208
	ds_read_b64_tr_b16 v[188:189], v3 offset:26624
	ds_read_b64_tr_b16 v[190:191], v3 offset:27136
	v_add_f32_e32 v2, v98, v2
	v_add_f32_e32 v2, v99, v2
	v_add_f32_e32 v2, v100, v2
	v_add_f32_e32 v2, v101, v2
	v_cvt_pk_bf16_f32 v148, v96, v97
	v_cvt_pk_bf16_f32 v149, v98, v99
	ds_read_b64_tr_b16 v[10:11], v4 offset:30720
	ds_read_b64_tr_b16 v[12:13], v4 offset:31232
	s_waitcnt lgkmcnt(14)
	v_mfma_f32_32x32x16_bf16 v[64:79], v[176:179], v[132:135], v[64:79]
	ds_read_b64_tr_b16 v[176:177], v3 offset:30720
	ds_read_b64_tr_b16 v[178:179], v3 offset:31232
	v_add_f32_e32 v2, v102, v2
	v_add_f32_e32 v2, v103, v2
	v_add_f32_e32 v2, v104, v2
	v_add_f32_e32 v2, v105, v2
	v_cvt_pk_bf16_f32 v150, v100, v101
	v_cvt_pk_bf16_f32 v151, v102, v103
	ds_read_b64_tr_b16 v[6:7], v4 offset:27648
	ds_read_b64_tr_b16 v[8:9], v4 offset:28160
	s_waitcnt lgkmcnt(14)
	v_mfma_f32_32x32x16_bf16 v[80:95], v[180:183], v[128:131], v[80:95]
	ds_read_b64_tr_b16 v[98:99], v3 offset:27648
	ds_read_b64_tr_b16 v[100:101], v3 offset:28160
	ds_read_b64_tr_b16 v[180:181], v3 offset:31744
	ds_read_b64_tr_b16 v[182:183], v3 offset:32256
	v_add_f32_e32 v2, v106, v2
	v_add_f32_e32 v2, v107, v2
	v_add_f32_e32 v2, v108, v2
	v_add_f32_e32 v15, v109, v2
	v_cvt_pk_bf16_f32 v140, v104, v105
	v_cvt_pk_bf16_f32 v141, v106, v107
	ds_read_b64_tr_b16 v[2:3], v4 offset:31744
	ds_read_b64_tr_b16 v[4:5], v4 offset:32256
	v_mfma_f32_32x32x16_bf16 v[64:79], v[172:175], v[128:131], v[64:79]
	v_add_f32_e32 v15, v110, v15
	v_add_f32_e32 v15, v111, v15
	v_add_f32_e32 v15, 0, v15
	v_cvt_pk_bf16_f32 v142, v108, v109
	v_cvt_pk_bf16_f32 v143, v110, v111
	v_max_f32_e32 v96, v81, v81
	v_max_f32_e32 v97, v80, v80
	s_waitcnt lgkmcnt(14)
	v_mfma_f32_32x32x16_bf16 v[224:239], v[156:159], v[192:195], v[224:239]
	v_max_f32_e32 v96, v97, v96
	s_nop 3
	v_max3_f32 v97, v82, v83, v65
	v_max3_f32 v96, v96, v64, v66
	v_max3_f32 v96, v96, v67, v84
	s_waitcnt lgkmcnt(14)
	v_mfma_f32_32x32x16_bf16 v[240:255], v[156:159], v[120:123], v[240:255]
	v_max3_f32 v97, v97, v86, v87
	v_max3_f32 v96, v96, v85, v68
	v_max3_f32 v97, v97, v70, v71
	v_max3_f32 v96, v96, v69, v88
	s_waitcnt lgkmcnt(14)
	v_mfma_f32_32x32x16_bf16 v[224:239], v[152:155], v[184:187], v[224:239]
	v_max3_f32 v97, v97, v90, v91
	v_max3_f32 v96, v96, v89, v72
	v_max3_f32 v97, v97, v74, v75
	v_max3_f32 v96, v96, v73, v92
	v_max3_f32 v97, v97, v94, v95
	s_waitcnt lgkmcnt(14)
	v_mfma_f32_32x32x16_bf16 v[240:255], v[152:155], v[124:127], v[240:255]
	v_max3_f32 v96, v96, v93, v76
	v_max3_f32 v97, v97, v78, v79
	v_add_f32_e32 v222, v14, v15
	v_max3_f32 v14, v96, v77, v97
	v_mov_b32_e32 v15, v14
	s_nop 1
	v_permlane32_swap_b32_e32 v14, v15
	s_waitcnt lgkmcnt(12)
	v_mfma_f32_32x32x16_bf16 v[224:239], v[148:151], v[188:191], v[224:239]
	v_max_f32_e32 v15, v15, v15
	v_max_f32_e32 v14, v14, v14
	s_add_i32 s2, s45, s61
	s_waitcnt lgkmcnt(8)
	v_mfma_f32_32x32x16_bf16 v[240:255], v[148:151], v[176:179], v[240:255]
	s_mov_b32 s3, m0
	s_mov_b32 m0, s2
	s_nop 0
	global_load_lds_dwordx4 v[202:203], off
	s_mov_b32 m0, s3
	v_max_f32_e32 v14, v14, v15
	s_add_i32 s2, s64, s62
	s_add_i32 s100, s64, s99
	s_waitcnt lgkmcnt(4)
	v_mfma_f32_32x32x16_bf16 v[224:239], v[140:143], v[98:101], v[224:239]
	s_mov_b32 s3, m0
	s_mov_b32 m0, s2
	s_nop 0
	global_load_lds_dwordx4 v[200:201], off
	s_waitcnt lgkmcnt(2)
	v_mfma_f32_32x32x16_bf16 v[240:255], v[140:143], v[180:183], v[240:255]
	s_mov_b32 m0, s100
	v_lshl_add_u64 v[96:97], v[200:201], 0, 64
	v_lshl_add_u64 v[96:97], v[96:97], 0, 64
	global_load_lds_dwordx4 v[96:97], off
	s_mov_b32 m0, s3
	v_cmp_lt_f32_e32 vcc, s52, v14
	s_cmp_lg_u64 vcc, 0
	s_cselect_b64 s[2:3], -1, 0
	s_cbranch_vccnz .LBB0_248
.LBB0_241:
	s_waitcnt lgkmcnt(14)
	v_mfma_f32_32x32x16_bf16 v[32:47], v[156:159], v[168:171], v[32:47]
	v_exp_f32_e32 v80, v80
	v_exp_f32_e32 v81, v81
	v_exp_f32_e32 v82, v82
	v_exp_f32_e32 v83, v83
	s_waitcnt lgkmcnt(12)
	v_mfma_f32_32x32x16_bf16 v[16:31], v[156:159], v[164:167], v[16:31]
	v_exp_f32_e32 v84, v84
	v_exp_f32_e32 v85, v85
	v_exp_f32_e32 v86, v86
	v_exp_f32_e32 v87, v87
	v_add_u32_e32 v14, s64, v219
	ds_read_b128 v[188:191], v14
	ds_read_b128 v[184:187], v14 offset:512
	s_waitcnt lgkmcnt(12)
	v_mfma_f32_32x32x16_bf16 v[32:47], v[152:155], v[160:163], v[32:47]
	v_exp_f32_e32 v88, v88
	v_exp_f32_e32 v89, v89
	v_exp_f32_e32 v90, v90
	v_exp_f32_e32 v91, v91
	ds_read_b128 v[180:183], v14 offset:2048
	ds_read_b128 v[176:179], v14 offset:2560
	s_waitcnt lgkmcnt(12)
	v_mfma_f32_32x32x16_bf16 v[16:31], v[152:155], v[116:119], v[16:31]
	v_exp_f32_e32 v92, v92
	v_exp_f32_e32 v93, v93
	v_exp_f32_e32 v94, v94
	v_exp_f32_e32 v95, v95
	ds_read_b128 v[172:175], v14 offset:4096
	ds_read_b128 v[168:171], v14 offset:4608
	s_waitcnt lgkmcnt(12)
	v_mfma_f32_32x32x16_bf16 v[32:47], v[148:151], v[112:115], v[32:47]
	v_exp_f32_e32 v64, v64
	v_exp_f32_e32 v65, v65
	v_exp_f32_e32 v66, v66
	v_exp_f32_e32 v67, v67
	ds_read_b128 v[164:167], v14 offset:6144
	ds_read_b128 v[160:163], v14 offset:6656
	s_waitcnt lgkmcnt(12)
	v_mfma_f32_32x32x16_bf16 v[16:31], v[148:151], v[10:13], v[16:31]
	v_exp_f32_e32 v68, v68
	v_exp_f32_e32 v69, v69
	v_exp_f32_e32 v70, v70
	v_exp_f32_e32 v71, v71
	s_waitcnt lgkmcnt(10)
	v_mfma_f32_32x32x16_bf16 v[32:47], v[140:143], v[6:9], v[32:47]
	v_exp_f32_e32 v72, v72
	v_exp_f32_e32 v73, v73
	v_exp_f32_e32 v74, v74
	v_exp_f32_e32 v75, v75
	s_waitcnt lgkmcnt(8)
	v_mfma_f32_32x32x16_bf16 v[16:31], v[140:143], v[2:5], v[16:31]
	v_exp_f32_e32 v76, v76
	v_exp_f32_e32 v77, v77
	v_exp_f32_e32 v78, v78
	v_exp_f32_e32 v79, v79
	s_waitcnt vmcnt(3) lgkmcnt(0)
	s_barrier
	s_andn2_b64 vcc, exec, s[2:3]
	s_cbranch_vccnz .LBB0_243
	s_waitcnt lgkmcnt(0)
	ds_read_b128 v[2:5], v0 offset:49248
	ds_read_b128 v[6:9], v0 offset:49216
	ds_read_b128 v[10:13], v0 offset:49184
	ds_read_b128 v[96:99], v0 offset:49152
	s_waitcnt lgkmcnt(3)
	v_pk_mul_f32 v[44:45], v[44:45], v[2:3]
	v_pk_mul_f32 v[236:237], v[236:237], v[2:3]
	s_waitcnt lgkmcnt(2)
	v_pk_mul_f32 v[40:41], v[40:41], v[6:7]
	v_pk_mul_f32 v[232:233], v[232:233], v[6:7]
	s_waitcnt lgkmcnt(1)
	v_pk_mul_f32 v[36:37], v[36:37], v[10:11]
	v_pk_mul_f32 v[228:229], v[228:229], v[10:11]
	v_pk_mul_f32 v[46:47], v[46:47], v[4:5]
	v_pk_mul_f32 v[238:239], v[238:239], v[4:5]
	v_pk_mul_f32 v[42:43], v[42:43], v[8:9]
	v_pk_mul_f32 v[234:235], v[234:235], v[8:9]
	v_pk_mul_f32 v[38:39], v[38:39], v[12:13]
	v_pk_mul_f32 v[230:231], v[230:231], v[12:13]
	s_waitcnt lgkmcnt(0)
	v_pk_mul_f32 v[34:35], v[34:35], v[98:99]
	v_pk_mul_f32 v[226:227], v[226:227], v[98:99]
	v_pk_mul_f32 v[32:33], v[32:33], v[96:97]
	v_pk_mul_f32 v[224:225], v[224:225], v[96:97]
	v_pk_mul_f32 v[28:29], v[28:29], v[2:3]
	v_pk_mul_f32 v[252:253], v[252:253], v[2:3]
	v_pk_mul_f32 v[24:25], v[24:25], v[6:7]
	v_pk_mul_f32 v[248:249], v[248:249], v[6:7]
	v_pk_mul_f32 v[20:21], v[20:21], v[10:11]
	v_pk_mul_f32 v[244:245], v[244:245], v[10:11]
	v_pk_mul_f32 v[30:31], v[30:31], v[4:5]
	v_pk_mul_f32 v[254:255], v[254:255], v[4:5]
	v_pk_mul_f32 v[26:27], v[26:27], v[8:9]
	v_pk_mul_f32 v[250:251], v[250:251], v[8:9]
	v_pk_mul_f32 v[22:23], v[22:23], v[12:13]
	v_pk_mul_f32 v[246:247], v[246:247], v[12:13]
	v_pk_mul_f32 v[18:19], v[18:19], v[98:99]
	v_pk_mul_f32 v[242:243], v[242:243], v[98:99]
	v_pk_mul_f32 v[16:17], v[16:17], v[96:97]
	v_pk_mul_f32 v[240:241], v[240:241], v[96:97]

.LBB0_1717:
	v_add_u32_e32 v0, s2, v221
	s_mov_b32 s98, s2
	ds_read_b64_tr_b16 v[192:193], v0 offset:24576
	ds_read_b64_tr_b16 v[194:195], v0 offset:25088
	s_waitcnt lgkmcnt(9)
	v_mfma_f32_32x32x16_bf16 v[112:127], v[188:191], v[144:147], v[48:63]
	v_add_f32_e32 v2, v80, v81
	v_add_f32_e32 v2, v82, v2
	v_add_f32_e32 v2, v83, v2
	v_add_f32_e32 v2, v84, v2
	v_add_f32_e32 v2, v85, v2
	v_cvt_pk_bf16_f32 v156, v80, v81
	v_cvt_pk_bf16_f32 v157, v82, v83
	ds_read_b64_tr_b16 v[188:189], v0 offset:28672
	ds_read_b64_tr_b16 v[190:191], v0 offset:29184
	s_waitcnt lgkmcnt(10)
	v_mfma_f32_32x32x16_bf16 v[96:111], v[184:187], v[144:147], v[48:63]
	v_add_f32_e32 v2, v86, v2
	v_add_f32_e32 v2, v87, v2
	v_add_f32_e32 v2, v88, v2
	v_add_f32_e32 v2, v89, v2
	v_cvt_pk_bf16_f32 v158, v84, v85
	v_cvt_pk_bf16_f32 v159, v86, v87
	ds_read_b64_tr_b16 v[184:185], v0 offset:25600
	ds_read_b64_tr_b16 v[186:187], v0 offset:26112
	s_waitcnt lgkmcnt(11)
	v_mfma_f32_32x32x16_bf16 v[112:127], v[180:183], v[136:139], v[112:127]
	v_add_u32_e32 v3, s98, v221
	v_add_u32_e32 v3, 0xf000, v3
	ds_read_b64_tr_b16 v[180:181], v3 offset:24576
	ds_read_b64_tr_b16 v[182:183], v3 offset:25088
	v_add_f32_e32 v2, v90, v2
	v_add_f32_e32 v2, v91, v2
	v_add_f32_e32 v2, v92, v2
	v_add_f32_e32 v2, v93, v2
	v_cvt_pk_bf16_f32 v152, v88, v89
	v_cvt_pk_bf16_f32 v153, v90, v91
	ds_read_b64_tr_b16 v[84:85], v0 offset:29696
	ds_read_b64_tr_b16 v[86:87], v0 offset:30208
	s_waitcnt lgkmcnt(12)
	v_mfma_f32_32x32x16_bf16 v[96:111], v[176:179], v[136:139], v[96:111]
	ds_read_b64_tr_b16 v[88:89], v3 offset:28672
	ds_read_b64_tr_b16 v[90:91], v3 offset:29184
	ds_read_b64_tr_b16 v[176:177], v3 offset:25600
	ds_read_b64_tr_b16 v[178:179], v3 offset:26112
	v_add_f32_e32 v2, v94, v2
	v_add_f32_e32 v2, v95, v2
	v_add_f32_e32 v2, v64, v2
	v_add_f32_e32 v2, v65, v2
	v_cvt_pk_bf16_f32 v154, v92, v93
	v_cvt_pk_bf16_f32 v155, v94, v95
	ds_read_b64_tr_b16 v[80:81], v0 offset:26624
	ds_read_b64_tr_b16 v[82:83], v0 offset:27136
	s_waitcnt lgkmcnt(13)
	v_mfma_f32_32x32x16_bf16 v[112:127], v[172:175], v[132:135], v[112:127]
	ds_read_b64_tr_b16 v[92:93], v3 offset:29696
	ds_read_b64_tr_b16 v[94:95], v3 offset:30208
	ds_read_b64_tr_b16 v[172:173], v3 offset:26624
	ds_read_b64_tr_b16 v[174:175], v3 offset:27136
	v_add_f32_e32 v2, v66, v2
	v_add_f32_e32 v2, v67, v2
	v_add_f32_e32 v2, v68, v2
	v_add_f32_e32 v2, v69, v2
	v_cvt_pk_bf16_f32 v148, v64, v65
	v_cvt_pk_bf16_f32 v149, v66, v67
	ds_read_b64_tr_b16 v[10:11], v0 offset:30720
	ds_read_b64_tr_b16 v[12:13], v0 offset:31232
	s_waitcnt lgkmcnt(14)
	v_mfma_f32_32x32x16_bf16 v[96:111], v[168:171], v[132:135], v[96:111]
	ds_read_b64_tr_b16 v[168:169], v3 offset:30720
	ds_read_b64_tr_b16 v[170:171], v3 offset:31232
	v_add_f32_e32 v2, v70, v2
	v_add_f32_e32 v2, v71, v2
	v_add_f32_e32 v2, v72, v2
	v_add_f32_e32 v2, v73, v2
	v_cvt_pk_bf16_f32 v150, v68, v69
	v_cvt_pk_bf16_f32 v151, v70, v71
	ds_read_b64_tr_b16 v[6:7], v0 offset:27648
	ds_read_b64_tr_b16 v[8:9], v0 offset:28160
	s_waitcnt lgkmcnt(14)
	v_mfma_f32_32x32x16_bf16 v[112:127], v[164:167], v[128:131], v[112:127]
	ds_read_b64_tr_b16 v[66:67], v3 offset:27648
	ds_read_b64_tr_b16 v[68:69], v3 offset:28160
	ds_read_b64_tr_b16 v[164:165], v3 offset:31744
	ds_read_b64_tr_b16 v[166:167], v3 offset:32256
	v_add_f32_e32 v2, v74, v2
	v_add_f32_e32 v2, v75, v2
	v_add_f32_e32 v2, v76, v2
	v_add_f32_e32 v14, v77, v2
	v_cvt_pk_bf16_f32 v140, v72, v73
	v_cvt_pk_bf16_f32 v141, v74, v75
	ds_read_b64_tr_b16 v[2:3], v0 offset:31744
	ds_read_b64_tr_b16 v[4:5], v0 offset:32256
	v_mfma_f32_32x32x16_bf16 v[96:111], v[160:163], v[128:131], v[96:111]
	v_add_f32_e32 v0, v78, v14
	v_add_f32_e32 v0, v79, v0
	v_add_f32_e32 v0, 0, v0
	v_cvt_pk_bf16_f32 v142, v76, v77
	v_cvt_pk_bf16_f32 v143, v78, v79
	v_lshl_add_u64 v[14:15], v[202:203], 0, s[26:27]
	s_add_i32 s2, s47, s61
	s_waitcnt lgkmcnt(14)
	v_mfma_f32_32x32x16_bf16 v[224:239], v[156:159], v[180:183], v[224:239]
	s_mov_b32 s3, m0
	s_mov_b32 m0, s2
	s_nop 0
	global_load_lds_dwordx4 v[14:15], off
	s_mov_b32 m0, s3
	v_lshl_add_u64 v[14:15], v[200:201], 0, s[26:27]
	s_add_i32 s2, s45, s62
	s_add_i32 s100, s45, s99
	s_waitcnt lgkmcnt(14)
	v_mfma_f32_32x32x16_bf16 v[240:255], v[156:159], v[88:91], v[240:255]
	s_mov_b32 s3, m0
	s_mov_b32 m0, s2
	s_nop 0
	global_load_lds_dwordx4 v[14:15], off
	s_waitcnt lgkmcnt(14)
	v_mfma_f32_32x32x16_bf16 v[224:239], v[152:155], v[176:179], v[224:239]
	s_mov_b32 m0, s100
	v_lshl_add_u64 v[64:65], v[14:15], 0, 64
	v_lshl_add_u64 v[64:65], v[64:65], 0, 64
	global_load_lds_dwordx4 v[64:65], off
	s_mov_b32 m0, s3
	v_max_f32_e32 v14, v113, v113
	v_max_f32_e32 v15, v112, v112
	s_waitcnt lgkmcnt(14)
	v_mfma_f32_32x32x16_bf16 v[240:255], v[152:155], v[92:95], v[240:255]
	v_max_f32_e32 v14, v15, v14
	v_max3_f32 v15, v114, v115, v97
	v_max3_f32 v14, v14, v96, v98
	v_max3_f32 v14, v14, v99, v116
	s_waitcnt lgkmcnt(12)
	v_mfma_f32_32x32x16_bf16 v[224:239], v[148:151], v[172:175], v[224:239]
	v_max3_f32 v15, v15, v118, v119
	v_max3_f32 v14, v14, v117, v100
	v_max3_f32 v15, v15, v102, v103
	v_max3_f32 v14, v14, v101, v120
	s_waitcnt lgkmcnt(8)
	v_mfma_f32_32x32x16_bf16 v[240:255], v[148:151], v[168:171], v[240:255]
	v_max3_f32 v15, v15, v122, v123
	v_max3_f32 v14, v14, v121, v104
	v_max3_f32 v15, v15, v106, v107
	v_max3_f32 v14, v14, v105, v124
	v_max3_f32 v15, v15, v126, v127
	s_waitcnt lgkmcnt(4)
	v_mfma_f32_32x32x16_bf16 v[224:239], v[140:143], v[66:69], v[224:239]
	v_max3_f32 v64, v14, v125, v108
	v_max3_f32 v15, v15, v110, v111
	v_add_f32_e32 v14, v223, v0
	v_max3_f32 v0, v64, v109, v15
	v_mov_b32_e32 v15, v0
	s_nop 1
	v_permlane32_swap_b32_e32 v0, v15
	s_waitcnt lgkmcnt(2)
	v_mfma_f32_32x32x16_bf16 v[240:255], v[140:143], v[164:167], v[240:255]
	v_max_f32_e32 v15, v15, v15
	v_max_f32_e32 v0, v0, v0
	v_max_f32_e32 v0, v0, v15
	v_cmp_lt_f32_e32 vcc, s52, v0
	s_cmp_lg_u64 vcc, 0
	s_cselect_b64 s[2:3], -1, 0
	s_cbranch_vccnz .LBB0_1725
.LBB0_1718:
	s_waitcnt lgkmcnt(14)
	v_mfma_f32_32x32x16_bf16 v[32:47], v[156:159], v[192:195], v[32:47]
	v_exp_f32_e32 v112, v112
	v_exp_f32_e32 v113, v113
	v_exp_f32_e32 v114, v114
	v_exp_f32_e32 v115, v115
	s_waitcnt lgkmcnt(12)
	v_mfma_f32_32x32x16_bf16 v[16:31], v[156:159], v[188:191], v[16:31]
	v_exp_f32_e32 v116, v116
	v_exp_f32_e32 v117, v117
	v_exp_f32_e32 v118, v118
	v_exp_f32_e32 v119, v119
	v_add_u32_e32 v0, s45, v220
	ds_read_b128 v[64:67], v0
	ds_read_b128 v[160:163], v0 offset:512
	s_waitcnt lgkmcnt(12)
	v_mfma_f32_32x32x16_bf16 v[32:47], v[152:155], v[184:187], v[32:47]
	v_exp_f32_e32 v120, v120
	v_exp_f32_e32 v121, v121
	v_exp_f32_e32 v122, v122
	v_exp_f32_e32 v123, v123
	ds_read_b128 v[192:195], v0 offset:2048
	ds_read_b128 v[184:187], v0 offset:2560
	s_waitcnt lgkmcnt(12)
	v_mfma_f32_32x32x16_bf16 v[16:31], v[152:155], v[84:87], v[16:31]
	v_exp_f32_e32 v124, v124
	v_exp_f32_e32 v125, v125
	v_exp_f32_e32 v126, v126
	v_exp_f32_e32 v127, v127
	ds_read_b128 v[188:191], v0 offset:4096
	ds_read_b128 v[176:179], v0 offset:4608
	s_waitcnt lgkmcnt(12)
	v_mfma_f32_32x32x16_bf16 v[32:47], v[148:151], v[80:83], v[32:47]
	v_exp_f32_e32 v96, v96
	v_exp_f32_e32 v97, v97
	v_exp_f32_e32 v98, v98
	v_exp_f32_e32 v99, v99
	ds_read_b128 v[180:183], v0 offset:6144
	ds_read_b128 v[172:175], v0 offset:6656
	s_waitcnt lgkmcnt(12)
	v_mfma_f32_32x32x16_bf16 v[16:31], v[148:151], v[10:13], v[16:31]
	v_exp_f32_e32 v100, v100
	v_exp_f32_e32 v101, v101
	v_exp_f32_e32 v102, v102
	v_exp_f32_e32 v103, v103
	s_waitcnt lgkmcnt(10)
	v_mfma_f32_32x32x16_bf16 v[32:47], v[140:143], v[6:9], v[32:47]
	v_exp_f32_e32 v104, v104
	v_exp_f32_e32 v105, v105
	v_exp_f32_e32 v106, v106
	v_exp_f32_e32 v107, v107
	s_waitcnt lgkmcnt(8)
	v_mfma_f32_32x32x16_bf16 v[16:31], v[140:143], v[2:5], v[16:31]
	v_exp_f32_e32 v108, v108
	v_exp_f32_e32 v109, v109
	v_exp_f32_e32 v110, v110
	v_exp_f32_e32 v111, v111
	s_waitcnt vmcnt(3) lgkmcnt(0)
	s_barrier
	s_andn2_b64 vcc, exec, s[2:3]
	v_add_u32_e32 v0, s60, v222
	s_cbranch_vccnz .LBB0_1720
	s_waitcnt lgkmcnt(0)
	ds_read_b128 v[2:5], v0 offset:49248
	ds_read_b128 v[6:9], v0 offset:49216
	ds_read_b128 v[10:13], v0 offset:49184
	ds_read_b128 v[68:71], v0 offset:49152
	s_waitcnt lgkmcnt(3)
	v_pk_mul_f32 v[44:45], v[44:45], v[2:3]
	v_pk_mul_f32 v[236:237], v[236:237], v[2:3]
	s_waitcnt lgkmcnt(2)
	v_pk_mul_f32 v[40:41], v[40:41], v[6:7]
	v_pk_mul_f32 v[232:233], v[232:233], v[6:7]
	s_waitcnt lgkmcnt(1)
	v_pk_mul_f32 v[36:37], v[36:37], v[10:11]
	v_pk_mul_f32 v[228:229], v[228:229], v[10:11]
	v_pk_mul_f32 v[46:47], v[46:47], v[4:5]
	v_pk_mul_f32 v[238:239], v[238:239], v[4:5]
	v_pk_mul_f32 v[42:43], v[42:43], v[8:9]
	v_pk_mul_f32 v[234:235], v[234:235], v[8:9]
	v_pk_mul_f32 v[38:39], v[38:39], v[12:13]
	v_pk_mul_f32 v[230:231], v[230:231], v[12:13]
	s_waitcnt lgkmcnt(0)
	v_pk_mul_f32 v[34:35], v[34:35], v[70:71]
	v_pk_mul_f32 v[226:227], v[226:227], v[70:71]
	v_pk_mul_f32 v[32:33], v[32:33], v[68:69]
	v_pk_mul_f32 v[224:225], v[224:225], v[68:69]
	v_pk_mul_f32 v[28:29], v[28:29], v[2:3]
	v_pk_mul_f32 v[252:253], v[252:253], v[2:3]
	v_pk_mul_f32 v[24:25], v[24:25], v[6:7]
	v_pk_mul_f32 v[248:249], v[248:249], v[6:7]
	v_pk_mul_f32 v[20:21], v[20:21], v[10:11]
	v_pk_mul_f32 v[244:245], v[244:245], v[10:11]
	v_pk_mul_f32 v[30:31], v[30:31], v[4:5]
	v_pk_mul_f32 v[254:255], v[254:255], v[4:5]
	v_pk_mul_f32 v[26:27], v[26:27], v[8:9]
	v_pk_mul_f32 v[250:251], v[250:251], v[8:9]
	v_pk_mul_f32 v[22:23], v[22:23], v[12:13]
	v_pk_mul_f32 v[246:247], v[246:247], v[12:13]
	v_pk_mul_f32 v[18:19], v[18:19], v[70:71]
	v_pk_mul_f32 v[242:243], v[242:243], v[70:71]
	v_pk_mul_f32 v[16:17], v[16:17], v[68:69]
	v_pk_mul_f32 v[240:241], v[240:241], v[68:69]
.LBB0_1720:
	s_add_i32 s2, s45, 0x2000
	s_cmpk_lg_i32 s45, 0x4000
	s_cselect_b32 s64, s2, 0
	v_add_u32_e32 v4, s47, v221
	s_mov_b32 s98, s47
	ds_read_b64_tr_b16 v[168:169], v4 offset:24576
	ds_read_b64_tr_b16 v[170:171], v4 offset:25088
	s_waitcnt lgkmcnt(9)
	v_mfma_f32_32x32x16_bf16 v[80:95], v[64:67], v[144:147], v[48:63]
	v_add_f32_e32 v2, v112, v113
	v_add_f32_e32 v2, v114, v2
	v_add_f32_e32 v2, v115, v2
	v_add_f32_e32 v2, v116, v2
	v_add_f32_e32 v2, v117, v2
	v_cvt_pk_bf16_f32 v156, v112, v113
	v_cvt_pk_bf16_f32 v157, v114, v115
	ds_read_b64_tr_b16 v[164:165], v4 offset:28672
	ds_read_b64_tr_b16 v[166:167], v4 offset:29184
	s_waitcnt lgkmcnt(10)
	v_mfma_f32_32x32x16_bf16 v[64:79], v[160:163], v[144:147], v[48:63]
	v_add_f32_e32 v2, v118, v2
	v_add_f32_e32 v2, v119, v2
	v_add_f32_e32 v2, v120, v2
	v_add_f32_e32 v2, v121, v2
	v_cvt_pk_bf16_f32 v158, v116, v117
	v_cvt_pk_bf16_f32 v159, v118, v119
	ds_read_b64_tr_b16 v[160:161], v4 offset:25600
	ds_read_b64_tr_b16 v[162:163], v4 offset:26112
	s_waitcnt lgkmcnt(11)
	v_mfma_f32_32x32x16_bf16 v[80:95], v[192:195], v[136:139], v[80:95]
	v_add_u32_e32 v3, s98, v221
	v_add_u32_e32 v3, 0xf000, v3
	ds_read_b64_tr_b16 v[192:193], v3 offset:24576
	ds_read_b64_tr_b16 v[194:195], v3 offset:25088
	v_add_f32_e32 v2, v122, v2
	v_add_f32_e32 v2, v123, v2
	v_add_f32_e32 v2, v124, v2
	v_add_f32_e32 v2, v125, v2
	v_cvt_pk_bf16_f32 v152, v120, v121
	v_cvt_pk_bf16_f32 v153, v122, v123
	ds_read_b64_tr_b16 v[116:117], v4 offset:29696
	ds_read_b64_tr_b16 v[118:119], v4 offset:30208
	s_waitcnt lgkmcnt(12)
	v_mfma_f32_32x32x16_bf16 v[64:79], v[184:187], v[136:139], v[64:79]
	ds_read_b64_tr_b16 v[120:121], v3 offset:28672
	ds_read_b64_tr_b16 v[122:123], v3 offset:29184
	ds_read_b64_tr_b16 v[184:185], v3 offset:25600
	ds_read_b64_tr_b16 v[186:187], v3 offset:26112
	v_add_f32_e32 v2, v126, v2
	v_add_f32_e32 v2, v127, v2
	v_add_f32_e32 v2, v96, v2
	v_add_f32_e32 v2, v97, v2
	v_cvt_pk_bf16_f32 v154, v124, v125
	v_cvt_pk_bf16_f32 v155, v126, v127
	ds_read_b64_tr_b16 v[112:113], v4 offset:26624
	ds_read_b64_tr_b16 v[114:115], v4 offset:27136
	s_waitcnt lgkmcnt(13)
	v_mfma_f32_32x32x16_bf16 v[80:95], v[188:191], v[132:135], v[80:95]
	ds_read_b64_tr_b16 v[124:125], v3 offset:29696
	ds_read_b64_tr_b16 v[126:127], v3 offset:30208
	ds_read_b64_tr_b16 v[188:189], v3 offset:26624
	ds_read_b64_tr_b16 v[190:191], v3 offset:27136
	v_add_f32_e32 v2, v98, v2
	v_add_f32_e32 v2, v99, v2
	v_add_f32_e32 v2, v100, v2
	v_add_f32_e32 v2, v101, v2
	v_cvt_pk_bf16_f32 v148, v96, v97
	v_cvt_pk_bf16_f32 v149, v98, v99
	ds_read_b64_tr_b16 v[10:11], v4 offset:30720
	ds_read_b64_tr_b16 v[12:13], v4 offset:31232
	s_waitcnt lgkmcnt(14)
	v_mfma_f32_32x32x16_bf16 v[64:79], v[176:179], v[132:135], v[64:79]
	ds_read_b64_tr_b16 v[176:177], v3 offset:30720
	ds_read_b64_tr_b16 v[178:179], v3 offset:31232
	v_add_f32_e32 v2, v102, v2
	v_add_f32_e32 v2, v103, v2
	v_add_f32_e32 v2, v104, v2
	v_add_f32_e32 v2, v105, v2
	v_cvt_pk_bf16_f32 v150, v100, v101
	v_cvt_pk_bf16_f32 v151, v102, v103
	ds_read_b64_tr_b16 v[6:7], v4 offset:27648
	ds_read_b64_tr_b16 v[8:9], v4 offset:28160
	s_waitcnt lgkmcnt(14)
	v_mfma_f32_32x32x16_bf16 v[80:95], v[180:183], v[128:131], v[80:95]
	ds_read_b64_tr_b16 v[98:99], v3 offset:27648
	ds_read_b64_tr_b16 v[100:101], v3 offset:28160
	ds_read_b64_tr_b16 v[180:181], v3 offset:31744
	ds_read_b64_tr_b16 v[182:183], v3 offset:32256
	v_add_f32_e32 v2, v106, v2
	v_add_f32_e32 v2, v107, v2
	v_add_f32_e32 v2, v108, v2
	v_add_f32_e32 v15, v109, v2
	v_cvt_pk_bf16_f32 v140, v104, v105
	v_cvt_pk_bf16_f32 v141, v106, v107
	ds_read_b64_tr_b16 v[2:3], v4 offset:31744
	ds_read_b64_tr_b16 v[4:5], v4 offset:32256
	v_mfma_f32_32x32x16_bf16 v[64:79], v[172:175], v[128:131], v[64:79]
	v_add_f32_e32 v15, v110, v15
	v_add_f32_e32 v15, v111, v15
	v_add_f32_e32 v15, 0, v15
	v_cvt_pk_bf16_f32 v142, v108, v109
	v_cvt_pk_bf16_f32 v143, v110, v111
	v_max_f32_e32 v96, v81, v81
	v_max_f32_e32 v97, v80, v80
	s_waitcnt lgkmcnt(14)
	v_mfma_f32_32x32x16_bf16 v[224:239], v[156:159], v[192:195], v[224:239]
	v_max_f32_e32 v96, v97, v96
	s_nop 3
	v_max3_f32 v97, v82, v83, v65
	v_max3_f32 v96, v96, v64, v66
	v_max3_f32 v96, v96, v67, v84
	s_waitcnt lgkmcnt(14)
	v_mfma_f32_32x32x16_bf16 v[240:255], v[156:159], v[120:123], v[240:255]
	v_max3_f32 v97, v97, v86, v87
	v_max3_f32 v96, v96, v85, v68
	v_max3_f32 v97, v97, v70, v71
	v_max3_f32 v96, v96, v69, v88
	s_waitcnt lgkmcnt(14)
	v_mfma_f32_32x32x16_bf16 v[224:239], v[152:155], v[184:187], v[224:239]
	v_max3_f32 v97, v97, v90, v91
	v_max3_f32 v96, v96, v89, v72
	v_max3_f32 v97, v97, v74, v75
	v_max3_f32 v96, v96, v73, v92
	v_max3_f32 v97, v97, v94, v95
	s_waitcnt lgkmcnt(14)
	v_mfma_f32_32x32x16_bf16 v[240:255], v[152:155], v[124:127], v[240:255]
	v_max3_f32 v96, v96, v93, v76
	v_max3_f32 v97, v97, v78, v79
	v_add_f32_e32 v223, v14, v15
	v_max3_f32 v14, v96, v77, v97
	v_mov_b32_e32 v15, v14
	s_nop 1
	v_permlane32_swap_b32_e32 v14, v15
	s_waitcnt lgkmcnt(12)
	v_mfma_f32_32x32x16_bf16 v[224:239], v[148:151], v[188:191], v[224:239]
	v_max_f32_e32 v15, v15, v15
	v_max_f32_e32 v14, v14, v14
	s_add_i32 s2, s45, s61
	s_waitcnt lgkmcnt(8)
	v_mfma_f32_32x32x16_bf16 v[240:255], v[148:151], v[176:179], v[240:255]
	s_mov_b32 s3, m0
	s_mov_b32 m0, s2
	s_nop 0
	global_load_lds_dwordx4 v[202:203], off
	s_mov_b32 m0, s3
	v_max_f32_e32 v14, v14, v15
	s_add_i32 s2, s64, s62
	s_add_i32 s100, s64, s99
	s_waitcnt lgkmcnt(4)
	v_mfma_f32_32x32x16_bf16 v[224:239], v[140:143], v[98:101], v[224:239]
	s_mov_b32 s3, m0
	s_mov_b32 m0, s2
	s_nop 0
	global_load_lds_dwordx4 v[200:201], off
	s_waitcnt lgkmcnt(2)
	v_mfma_f32_32x32x16_bf16 v[240:255], v[140:143], v[180:183], v[240:255]
	s_mov_b32 m0, s100
	v_lshl_add_u64 v[96:97], v[200:201], 0, 64
	v_lshl_add_u64 v[96:97], v[96:97], 0, 64
	global_load_lds_dwordx4 v[96:97], off
	s_mov_b32 m0, s3
	v_cmp_lt_f32_e32 vcc, s52, v14
	s_cmp_lg_u64 vcc, 0
	s_cselect_b64 s[2:3], -1, 0
	s_cbranch_vccnz .LBB0_1728
.LBB0_1721:
	s_waitcnt lgkmcnt(14)
	v_mfma_f32_32x32x16_bf16 v[32:47], v[156:159], v[168:171], v[32:47]
	v_exp_f32_e32 v80, v80
	v_exp_f32_e32 v81, v81
	v_exp_f32_e32 v82, v82
	v_exp_f32_e32 v83, v83
	s_waitcnt lgkmcnt(12)
	v_mfma_f32_32x32x16_bf16 v[16:31], v[156:159], v[164:167], v[16:31]
	v_exp_f32_e32 v84, v84
	v_exp_f32_e32 v85, v85
	v_exp_f32_e32 v86, v86
	v_exp_f32_e32 v87, v87
	v_add_u32_e32 v14, s64, v220
	ds_read_b128 v[188:191], v14
	ds_read_b128 v[184:187], v14 offset:512
	s_waitcnt lgkmcnt(12)
	v_mfma_f32_32x32x16_bf16 v[32:47], v[152:155], v[160:163], v[32:47]
	v_exp_f32_e32 v88, v88
	v_exp_f32_e32 v89, v89
	v_exp_f32_e32 v90, v90
	v_exp_f32_e32 v91, v91
	ds_read_b128 v[180:183], v14 offset:2048
	ds_read_b128 v[176:179], v14 offset:2560
	s_waitcnt lgkmcnt(12)
	v_mfma_f32_32x32x16_bf16 v[16:31], v[152:155], v[116:119], v[16:31]
	v_exp_f32_e32 v92, v92
	v_exp_f32_e32 v93, v93
	v_exp_f32_e32 v94, v94
	v_exp_f32_e32 v95, v95
	ds_read_b128 v[172:175], v14 offset:4096
	ds_read_b128 v[168:171], v14 offset:4608
	s_waitcnt lgkmcnt(12)
	v_mfma_f32_32x32x16_bf16 v[32:47], v[148:151], v[112:115], v[32:47]
	v_exp_f32_e32 v64, v64
	v_exp_f32_e32 v65, v65
	v_exp_f32_e32 v66, v66
	v_exp_f32_e32 v67, v67
	ds_read_b128 v[164:167], v14 offset:6144
	ds_read_b128 v[160:163], v14 offset:6656
	s_waitcnt lgkmcnt(12)
	v_mfma_f32_32x32x16_bf16 v[16:31], v[148:151], v[10:13], v[16:31]
	v_exp_f32_e32 v68, v68
	v_exp_f32_e32 v69, v69
	v_exp_f32_e32 v70, v70
	v_exp_f32_e32 v71, v71
	s_waitcnt lgkmcnt(10)
	v_mfma_f32_32x32x16_bf16 v[32:47], v[140:143], v[6:9], v[32:47]
	v_exp_f32_e32 v72, v72
	v_exp_f32_e32 v73, v73
	v_exp_f32_e32 v74, v74
	v_exp_f32_e32 v75, v75
	s_waitcnt lgkmcnt(8)
	v_mfma_f32_32x32x16_bf16 v[16:31], v[140:143], v[2:5], v[16:31]
	v_exp_f32_e32 v76, v76
	v_exp_f32_e32 v77, v77
	v_exp_f32_e32 v78, v78
	v_exp_f32_e32 v79, v79
	s_waitcnt vmcnt(3) lgkmcnt(0)
	s_barrier
	s_andn2_b64 vcc, exec, s[2:3]
	s_cbranch_vccnz .LBB0_1723
	s_waitcnt lgkmcnt(0)
	ds_read_b128 v[2:5], v0 offset:49248
	ds_read_b128 v[6:9], v0 offset:49216
	ds_read_b128 v[10:13], v0 offset:49184
	ds_read_b128 v[96:99], v0 offset:49152
	s_waitcnt lgkmcnt(3)
	v_pk_mul_f32 v[44:45], v[44:45], v[2:3]
	v_pk_mul_f32 v[236:237], v[236:237], v[2:3]
	s_waitcnt lgkmcnt(2)
	v_pk_mul_f32 v[40:41], v[40:41], v[6:7]
	v_pk_mul_f32 v[232:233], v[232:233], v[6:7]
	s_waitcnt lgkmcnt(1)
	v_pk_mul_f32 v[36:37], v[36:37], v[10:11]
	v_pk_mul_f32 v[228:229], v[228:229], v[10:11]
	v_pk_mul_f32 v[46:47], v[46:47], v[4:5]
	v_pk_mul_f32 v[238:239], v[238:239], v[4:5]
	v_pk_mul_f32 v[42:43], v[42:43], v[8:9]
	v_pk_mul_f32 v[234:235], v[234:235], v[8:9]
	v_pk_mul_f32 v[38:39], v[38:39], v[12:13]
	v_pk_mul_f32 v[230:231], v[230:231], v[12:13]
	s_waitcnt lgkmcnt(0)
	v_pk_mul_f32 v[34:35], v[34:35], v[98:99]
	v_pk_mul_f32 v[226:227], v[226:227], v[98:99]
	v_pk_mul_f32 v[32:33], v[32:33], v[96:97]
	v_pk_mul_f32 v[224:225], v[224:225], v[96:97]
	v_pk_mul_f32 v[28:29], v[28:29], v[2:3]
	v_pk_mul_f32 v[252:253], v[252:253], v[2:3]
	v_pk_mul_f32 v[24:25], v[24:25], v[6:7]
	v_pk_mul_f32 v[248:249], v[248:249], v[6:7]
	v_pk_mul_f32 v[20:21], v[20:21], v[10:11]
	v_pk_mul_f32 v[244:245], v[244:245], v[10:11]
	v_pk_mul_f32 v[30:31], v[30:31], v[4:5]
	v_pk_mul_f32 v[254:255], v[254:255], v[4:5]
	v_pk_mul_f32 v[26:27], v[26:27], v[8:9]
	v_pk_mul_f32 v[250:251], v[250:251], v[8:9]
	v_pk_mul_f32 v[22:23], v[22:23], v[12:13]
	v_pk_mul_f32 v[246:247], v[246:247], v[12:13]
	v_pk_mul_f32 v[18:19], v[18:19], v[98:99]
	v_pk_mul_f32 v[242:243], v[242:243], v[98:99]
	v_pk_mul_f32 v[16:17], v[16:17], v[96:97]
	v_pk_mul_f32 v[240:241], v[240:241], v[96:97]
